# SB: pg-select as a multiply under EXEC = lower half-wave (no cndmask), dead-flag check with two b128 reads
# baseline (speedup 1.0000x reference)
;     __device__ __forceinline__ void issue4(const bf16* k, const bf16* v, size_t pitch, int stage) const {
;         const size_t o = (size_t)r8 * pitch + c8 * 8; const unsigned d = base + (unsigned)stage * (2u * STG_BYTES);
;         glds16(k + o, (unsigned)__builtin_amdgcn_readfirstlane(d));
;         glds16(v + o, (unsigned)__builtin_amdgcn_readfirstlane(d + 8192u));
;         glds16(k + o + 64, (unsigned)__builtin_amdgcn_readfirstlane(d + 16384u));
;         glds16(v + o + 64, (unsigned)__builtin_amdgcn_readfirstlane(d + 24576u));
;     }
; __device__ __forceinline__ void sb_unit(const Params& p, LAS unsigned char* lds, int b, int hp, int qb, int tid, int lane, int wave) {
;     ...
;         if (it > 0) { int alld = 1;
; #pragma unroll
;             for (int w = 0; w < 8; ++w) alld &= flags[((it - 1) & 1) * 8 + w];
;             if (alld) break; }
;         if (it + 3 < nt) rg.issue4(Kb + (size_t)(j - 3) * 64 * ZW, Vb + (size_t)(j - 3) * 64 * ZW, ZW, (it + 3) & 3);
.LBB0_619:
	s_and_b32 s0, s11, 8
	s_xor_b32 s4, s0, 8
	s_lshl_b32 s4, s4, 2
	s_add_i32 s4, s4, 0x21080
	v_mov_b32_e32 v36, s4
	ds_read_b128 v[40:43], v36
	ds_read_b128 v[44:47], v36 offset:16
	s_waitcnt lgkmcnt(0)
	v_and_b32_e32 v40, v40, v41
	v_and_b32_e32 v42, v42, v43
	v_and_b32_e32 v44, v44, v45
	v_and_b32_e32 v46, v46, v47
	v_and_b32_e32 v40, v40, v42
	v_and_b32_e32 v44, v44, v46
	v_and_b32_e32 v36, v40, v44
	v_and_b32_e32 v36, 1, v36
	v_cmp_eq_u32_e64 s[22:23], 1, v36
	s_and_b64 vcc, exec, s[22:23]
	s_cbranch_vccnz .LBB0_610
	s_cmp_ge_u32 s10, s8
	s_cbranch_scc1 .LBB0_622
	s_and_b32 s4, s9, 0x18000
	s_add_i32 s4, s4, s92
	v_lshl_add_u64 v[36:37], v[88:89], 0, v[2:3]
	s_mov_b32 s5, m0
	s_mov_b32 m0, s4
	s_nop 0
	global_load_lds_dwordx4 v[36:37], off
	s_mov_b32 m0, s5
	v_lshl_add_u64 v[38:39], v[90:91], 0, v[2:3]
	s_add_i32 s5, s4, 0x2000
	s_mov_b32 s26, m0
	s_mov_b32 m0, s5
	s_nop 0
	global_load_lds_dwordx4 v[38:39], off
	s_mov_b32 m0, s26
	v_lshl_add_u64 v[36:37], v[36:37], 0, s[6:7]
	s_add_i32 s5, s4, 0x4000
	s_mov_b32 s26, m0
	s_mov_b32 m0, s5
	s_nop 0
	global_load_lds_dwordx4 v[36:37], off
	s_mov_b32 m0, s26
	v_lshl_add_u64 v[36:37], v[38:39], 0, s[6:7]
	s_addk_i32 s4, 0x6000
	s_mov_b32 s5, m0
	s_mov_b32 m0, s4
	s_nop 0
	global_load_lds_dwordx4 v[36:37], off
	s_mov_b32 m0, s5

; __device__ __forceinline__ float ex2(float x) { return __builtin_amdgcn_exp2f(x); }
; __device__ __forceinline__ float rcp(float x) { return __builtin_amdgcn_rcpf(x); }
; template <bool MK> __device__ __forceinline__ void sb_scan(f32x16& s0, f32x16& s1, int db, int hi, float& R) {
;             f32x16 k0, k1;
; #pragma unroll
;             for (int r = 0; r < 16; ++r) {
;                 const float e0 = ex2(fminf(s0[r], 80.f)), e1 = ex2(fminf(s1[r], 80.f));
;                 const float p0 = rcp(1.0f + e0), p1 = rcp(1.0f + e1);
;                 s0[r] = e0 * p0; s1[r] = e1 * p1;
;                 k0[r] = (!MK || KKOF(0, r) < db) ? p0 : 1.0f; k1[r] = (!MK || KKOF(1, r) < db) ? p1 : 1.0f;
;             }
;             float g4[8], pg[8], E[8];
; #pragma unroll
;             for (int k4 = 0; k4 < 4; ++k4) { g4[k4] = (k0[4 * k4] * k0[4 * k4 + 1]) * (k0[4 * k4 + 2] * k0[4 * k4 + 3]); g4[4 + k4] = (k1[4 * k4] * k1[4 * k4 + 1]) * (k1[4 * k4 + 2] * k1[4 * k4 + 3]); }
; #pragma unroll
;             for (int G = 0; G < 8; ++G) pg[G] = __shfl_xor(g4[G], 32);
;             E[7] = 1.0f;
; #pragma unroll
;             for (int G = 6; G >= 0; --G) E[G] = E[G + 1] * (g4[G + 1] * pg[G + 1]);
;             const float T = E[0] * (g4[0] * pg[0]);
.LBB0_626:
	s_andn2_b64 vcc, exec, s[24:25]
	s_cbranch_vccnz .LBB0_628
	v_exp_f32_e32 v124, v232
	v_exp_f32_e32 v126, v231
	v_exp_f32_e32 v128, v229
	v_exp_f32_e32 v130, v227
	v_exp_f32_e32 v125, v225
	v_exp_f32_e32 v127, v223
	v_exp_f32_e32 v129, v221
	v_exp_f32_e32 v131, v219
	v_add_f32_e32 v92, 1.0, v124
	v_add_f32_e32 v94, 1.0, v126
	v_add_f32_e32 v96, 1.0, v128
	v_add_f32_e32 v98, 1.0, v130
	v_add_f32_e32 v93, 1.0, v125
	v_add_f32_e32 v95, 1.0, v127
	v_add_f32_e32 v97, 1.0, v129
	v_add_f32_e32 v99, 1.0, v131
	v_rcp_f32_e32 v92, v92
	v_rcp_f32_e32 v94, v94
	v_rcp_f32_e32 v96, v96
	v_rcp_f32_e32 v98, v98
	v_rcp_f32_e32 v93, v93
	v_rcp_f32_e32 v95, v95
	v_rcp_f32_e32 v97, v97
	v_rcp_f32_e32 v99, v99
	v_exp_f32_e32 v132, v216
	v_exp_f32_e32 v134, v214
	v_exp_f32_e32 v136, v212
	v_exp_f32_e32 v138, v210
	v_exp_f32_e32 v133, v208
	v_exp_f32_e32 v135, v206
	v_exp_f32_e32 v137, v204
	v_exp_f32_e32 v139, v202
	v_add_f32_e32 v100, 1.0, v132
	v_add_f32_e32 v102, 1.0, v134
	v_add_f32_e32 v104, 1.0, v136
	v_add_f32_e32 v106, 1.0, v138
	v_add_f32_e32 v101, 1.0, v133
	v_add_f32_e32 v103, 1.0, v135
	v_add_f32_e32 v105, 1.0, v137
	v_add_f32_e32 v107, 1.0, v139
	v_rcp_f32_e32 v100, v100
	v_rcp_f32_e32 v102, v102
	v_rcp_f32_e32 v104, v104
	v_rcp_f32_e32 v106, v106
	v_rcp_f32_e32 v101, v101
	v_rcp_f32_e32 v103, v103
	v_rcp_f32_e32 v105, v105
	v_rcp_f32_e32 v107, v107
	v_exp_f32_e32 v140, v233
	v_exp_f32_e32 v142, v230
	v_exp_f32_e32 v144, v228
	v_exp_f32_e32 v146, v226
	v_exp_f32_e32 v141, v224
	v_exp_f32_e32 v143, v222
	v_exp_f32_e32 v145, v220
	v_exp_f32_e32 v147, v217
	v_add_f32_e32 v108, 1.0, v140
	v_add_f32_e32 v110, 1.0, v142
	v_add_f32_e32 v112, 1.0, v144
	v_add_f32_e32 v114, 1.0, v146
	v_add_f32_e32 v109, 1.0, v141
	v_add_f32_e32 v111, 1.0, v143
	v_add_f32_e32 v113, 1.0, v145
	v_add_f32_e32 v115, 1.0, v147
	v_rcp_f32_e32 v108, v108
	v_rcp_f32_e32 v110, v110
	v_rcp_f32_e32 v112, v112
	v_rcp_f32_e32 v114, v114
	v_rcp_f32_e32 v109, v109
	v_rcp_f32_e32 v111, v111
	v_rcp_f32_e32 v113, v113
	v_rcp_f32_e32 v115, v115
	v_exp_f32_e32 v148, v215
	v_exp_f32_e32 v150, v213
	v_exp_f32_e32 v152, v211
	v_exp_f32_e32 v154, v209
	v_exp_f32_e32 v149, v207
	v_exp_f32_e32 v151, v205
	v_exp_f32_e32 v153, v203
	v_exp_f32_e32 v155, v187
	v_add_f32_e32 v116, 1.0, v148
	v_add_f32_e32 v118, 1.0, v150
	v_add_f32_e32 v120, 1.0, v152
	v_add_f32_e32 v122, 1.0, v154
	v_add_f32_e32 v117, 1.0, v149
	v_add_f32_e32 v119, 1.0, v151
	v_add_f32_e32 v121, 1.0, v153
	v_add_f32_e32 v123, 1.0, v155
	v_rcp_f32_e32 v116, v116
	v_rcp_f32_e32 v118, v118
	v_rcp_f32_e32 v120, v120
	v_rcp_f32_e32 v122, v122
	v_rcp_f32_e32 v117, v117
	v_rcp_f32_e32 v119, v119
	v_rcp_f32_e32 v121, v121
	v_rcp_f32_e32 v123, v123
	v_pk_mul_f32 v[162:163], v[116:117], v[118:119]
	v_pk_mul_f32 v[42:43], v[120:121], v[122:123]
	v_pk_mul_f32 v[162:163], v[162:163], v[42:43]
	ds_bpermute_b32 v50, v201, v162
	ds_bpermute_b32 v51, v201, v163
	v_pk_mul_f32 v[160:161], v[108:109], v[110:111]
	v_pk_mul_f32 v[40:41], v[112:113], v[114:115]
	v_pk_mul_f32 v[160:161], v[160:161], v[40:41]
	ds_bpermute_b32 v48, v201, v160
	ds_bpermute_b32 v49, v201, v161
	v_pk_mul_f32 v[158:159], v[100:101], v[102:103]
	v_pk_mul_f32 v[38:39], v[104:105], v[106:107]
	v_pk_mul_f32 v[158:159], v[158:159], v[38:39]
	ds_bpermute_b32 v46, v201, v158
	ds_bpermute_b32 v47, v201, v159
	v_pk_mul_f32 v[156:157], v[92:93], v[94:95]
	v_pk_mul_f32 v[36:37], v[96:97], v[98:99]
	v_pk_mul_f32 v[156:157], v[156:157], v[36:37]
	ds_bpermute_b32 v44, v201, v156
	ds_bpermute_b32 v45, v201, v157
	v_pk_mul_f32 v[124:125], v[124:125], v[92:93]
	v_pk_mul_f32 v[126:127], v[126:127], v[94:95]
	v_pk_mul_f32 v[128:129], v[128:129], v[96:97]
	v_pk_mul_f32 v[130:131], v[130:131], v[98:99]
	v_pk_mul_f32 v[132:133], v[132:133], v[100:101]
	v_pk_mul_f32 v[134:135], v[134:135], v[102:103]
	v_pk_mul_f32 v[136:137], v[136:137], v[104:105]
	v_pk_mul_f32 v[138:139], v[138:139], v[106:107]
	v_pk_mul_f32 v[140:141], v[140:141], v[108:109]
	v_pk_mul_f32 v[142:143], v[142:143], v[110:111]
	v_pk_mul_f32 v[144:145], v[144:145], v[112:113]
	v_pk_mul_f32 v[146:147], v[146:147], v[114:115]
	v_pk_mul_f32 v[148:149], v[148:149], v[116:117]
	v_pk_mul_f32 v[150:151], v[150:151], v[118:119]
	v_pk_mul_f32 v[152:153], v[152:153], v[120:121]
	v_pk_mul_f32 v[154:155], v[154:155], v[122:123]
	s_waitcnt lgkmcnt(0)
; #define PACK_P(pw, s0, s1) do { _Pragma("unroll") for (int r_ = 0; r_ < 8; ++r_) { pw[r_] = pk2(s0[2 * r_], s0[2 * r_ + 1]); pw[8 + r_] = pk2(s1[2 * r_], s1[2 * r_ + 1]); } } while (0)
; template <bool MK> __device__ __forceinline__ void sb_scan(f32x16& s0, f32x16& s1, int db, int hi, float& R) {
;     ...
;             E[7] = 1.0f;
; #pragma unroll
;             for (int G = 6; G >= 0; --G) E[G] = E[G + 1] * (g4[G + 1] * pg[G + 1]);
;             const float T = E[0] * (g4[0] * pg[0]);
; #pragma unroll
;             for (int G = 0; G < 8; ++G) {
;                 const float base = R * E[G] * (hi == 0 ? pg[G] : 1.0f);
;                 const int k4 = G & 3;
;                 if (G < 4) {
;                     const float u3 = base, u2 = u3 * k0[4 * k4 + 3], u1 = u2 * k0[4 * k4 + 2], u0 = u1 * k0[4 * k4 + 1];
;                     s0[4 * k4 + 3] = (!MK || KKOF(0, 4 * k4 + 3) < db) ? s0[4 * k4 + 3] * u3 : 0.f;
;                     s0[4 * k4 + 2] = (!MK || KKOF(0, 4 * k4 + 2) < db) ? s0[4 * k4 + 2] * u2 : 0.f;
;                     s0[4 * k4 + 1] = (!MK || KKOF(0, 4 * k4 + 1) < db) ? s0[4 * k4 + 1] * u1 : 0.f;
;                     s0[4 * k4 + 0] = (!MK || KKOF(0, 4 * k4 + 0) < db) ? s0[4 * k4 + 0] * u0 : 0.f;
;                 } else {
;                     const float u3 = base, u2 = u3 * k1[4 * k4 + 3], u1 = u2 * k1[4 * k4 + 2], u0 = u1 * k1[4 * k4 + 1];
;                     s1[4 * k4 + 3] = (!MK || KKOF(1, 4 * k4 + 3) < db) ? s1[4 * k4 + 3] * u3 : 0.f;
;                     s1[4 * k4 + 2] = (!MK || KKOF(1, 4 * k4 + 2) < db) ? s1[4 * k4 + 2] * u2 : 0.f;
;                     s1[4 * k4 + 1] = (!MK || KKOF(1, 4 * k4 + 1) < db) ? s1[4 * k4 + 1] * u1 : 0.f;
;                     s1[4 * k4 + 0] = (!MK || KKOF(1, 4 * k4 + 0) < db) ? s1[4 * k4 + 0] * u0 : 0.f;
;                 }
;             }
;             R *= T;
; __device__ __forceinline__ void sb_unit(const Params& p, LAS unsigned char* lds, int b, int hp, int qb, int tid, int lane, int wave) {
;     ...
;             unsigned pw[16]; PACK_P(pw, s0, s1);
;             pv_tile_tr(stg + 8192, pw, tra, o0, o1);
;             dead = __all(R < 1.0e-44f);
	v_add3_u32 v165, s4, v182, v183
	v_add_u32_e32 v86, v165, v184
	v_add_u32_e32 v165, v165, v185
	ds_read_b64_tr_b16 v[202:203], v86 offset:8192
	ds_read_b64_tr_b16 v[204:205], v86 offset:9216
	ds_read_b64_tr_b16 v[206:207], v165 offset:8192
	ds_read_b64_tr_b16 v[208:209], v165 offset:9216
	ds_read_b64_tr_b16 v[210:211], v86 offset:10240
	ds_read_b64_tr_b16 v[212:213], v86 offset:11264
	ds_read_b64_tr_b16 v[214:215], v165 offset:10240
	ds_read_b64_tr_b16 v[216:217], v165 offset:11264
	v_pk_mul_f32 v[162:163], v[162:163], v[50:51]
	v_pk_mul_f32 v[160:161], v[160:161], v[48:49]
	v_pk_mul_f32 v[158:159], v[158:159], v[46:47]
	v_pk_mul_f32 v[156:157], v[156:157], v[44:45]
	v_mov_b32_e32 v42, v163
	v_mov_b32_e32 v43, 1.0
	v_mul_f32_e32 v41, v42, v162
	v_mul_f32_e32 v40, v41, v161
	v_mul_f32_e32 v39, v40, v160
	v_mul_f32_e32 v38, v39, v159
	v_mul_f32_e32 v37, v38, v158
	v_mul_f32_e32 v36, v37, v157
	v_mul_f32_e32 v164, v36, v156
	v_pk_mul_f32 v[36:37], v[86:87], v[36:37] op_sel:[1,0]
	v_pk_mul_f32 v[38:39], v[86:87], v[38:39] op_sel:[1,0]
	v_pk_mul_f32 v[40:41], v[86:87], v[40:41] op_sel:[1,0]
	v_pk_mul_f32 v[42:43], v[86:87], v[42:43] op_sel:[1,0]
	s_mov_b64 exec, s[18:19]
	v_pk_mul_f32 v[36:37], v[36:37], v[44:45]
	v_pk_mul_f32 v[38:39], v[38:39], v[46:47]
	v_pk_mul_f32 v[40:41], v[40:41], v[48:49]
	v_pk_mul_f32 v[42:43], v[42:43], v[50:51]
	s_mov_b64 exec, -1
	v_pk_mul_f32 v[98:99], v[36:37], v[98:99]
	v_pk_mul_f32 v[106:107], v[38:39], v[106:107]
	v_pk_mul_f32 v[114:115], v[40:41], v[114:115]
	v_pk_mul_f32 v[122:123], v[42:43], v[122:123]
	v_pk_mul_f32 v[130:131], v[130:131], v[36:37]
	v_pk_mul_f32 v[138:139], v[138:139], v[38:39]
	v_pk_mul_f32 v[146:147], v[146:147], v[40:41]
	v_pk_mul_f32 v[154:155], v[154:155], v[42:43]
	v_pk_mul_f32 v[96:97], v[98:99], v[96:97]
	v_pk_mul_f32 v[104:105], v[106:107], v[104:105]
	v_pk_mul_f32 v[112:113], v[114:115], v[112:113]
	v_pk_mul_f32 v[120:121], v[122:123], v[120:121]
	v_pk_mul_f32 v[128:129], v[128:129], v[98:99]
	v_pk_mul_f32 v[136:137], v[136:137], v[106:107]
	v_pk_mul_f32 v[144:145], v[144:145], v[114:115]
	v_pk_mul_f32 v[152:153], v[152:153], v[122:123]
	v_pk_mul_f32 v[94:95], v[96:97], v[94:95]
	v_pk_mul_f32 v[102:103], v[104:105], v[102:103]
	v_pk_mul_f32 v[110:111], v[112:113], v[110:111]
	v_pk_mul_f32 v[118:119], v[120:121], v[118:119]
	v_pk_mul_f32 v[126:127], v[126:127], v[96:97]
	v_pk_mul_f32 v[134:135], v[134:135], v[104:105]
	v_pk_mul_f32 v[142:143], v[142:143], v[112:113]
	v_pk_mul_f32 v[150:151], v[150:151], v[120:121]
	v_pk_mul_f32 v[124:125], v[124:125], v[94:95]
	v_pk_mul_f32 v[132:133], v[132:133], v[102:103]
	v_pk_mul_f32 v[140:141], v[140:141], v[110:111]
	v_pk_mul_f32 v[148:149], v[148:149], v[118:119]
	v_cvt_pk_bf16_f32 v52, v124, v126
	v_cvt_pk_bf16_f32 v53, v128, v130
	v_cvt_pk_bf16_f32 v54, v125, v127
	v_cvt_pk_bf16_f32 v55, v129, v131
	v_cvt_pk_bf16_f32 v56, v132, v134
	v_cvt_pk_bf16_f32 v57, v136, v138
	v_cvt_pk_bf16_f32 v58, v133, v135
	v_cvt_pk_bf16_f32 v59, v137, v139
	v_cvt_pk_bf16_f32 v60, v140, v142
	v_cvt_pk_bf16_f32 v61, v144, v146
	v_cvt_pk_bf16_f32 v62, v141, v143
	v_cvt_pk_bf16_f32 v63, v145, v147
	v_cvt_pk_bf16_f32 v64, v148, v150
	v_cvt_pk_bf16_f32 v65, v152, v154
	v_cvt_pk_bf16_f32 v66, v149, v151
	v_cvt_pk_bf16_f32 v67, v153, v155
	v_mul_f32_e32 v87, v87, v164
	v_cmp_gt_f32_e32 vcc, 7, v87
	s_cmp_eq_u64 vcc, exec
	s_cselect_b64 s[24:25], -1, 0
	s_waitcnt lgkmcnt(6)
	v_mfma_f32_32x32x16_bf16 v[20:35], v[202:205], v[52:55], v[20:35]
	s_waitcnt lgkmcnt(4)
	v_mfma_f32_32x32x16_bf16 v[4:19], v[206:209], v[52:55], v[4:19]
	ds_read_b64_tr_b16 v[202:203], v86 offset:12288
	ds_read_b64_tr_b16 v[204:205], v86 offset:13312
	ds_read_b64_tr_b16 v[206:207], v165 offset:12288
	ds_read_b64_tr_b16 v[208:209], v165 offset:13312
	s_waitcnt lgkmcnt(6)
	v_mfma_f32_32x32x16_bf16 v[20:35], v[210:213], v[56:59], v[20:35]
	s_waitcnt lgkmcnt(4)
	v_mfma_f32_32x32x16_bf16 v[4:19], v[214:217], v[56:59], v[4:19]
	ds_read_b64_tr_b16 v[210:211], v86 offset:14336
	ds_read_b64_tr_b16 v[212:213], v86 offset:15360
	ds_read_b64_tr_b16 v[214:215], v165 offset:14336
	ds_read_b64_tr_b16 v[216:217], v165 offset:15360
	s_waitcnt lgkmcnt(6)
	v_mfma_f32_32x32x16_bf16 v[20:35], v[202:205], v[60:63], v[20:35]
	s_waitcnt lgkmcnt(4)
	v_mfma_f32_32x32x16_bf16 v[4:19], v[206:209], v[60:63], v[4:19]
	s_waitcnt lgkmcnt(2)
	v_mfma_f32_32x32x16_bf16 v[20:35], v[210:213], v[64:67], v[20:35]
	s_waitcnt lgkmcnt(0)
	v_mfma_f32_32x32x16_bf16 v[4:19], v[214:217], v[64:67], v[4:19]
	s_branch .LBB0_629
